# plus: replaced the cooperative-groups grid.sync after the weight-conversion phase with the kernel's own XCD-hierarchical barrier
# speedup vs baseline: 1.0058x; 1.0058x over previous
; #define LAS __attribute__((address_space(3)))
; #define GSYNC() xcd_barrier(xb)
; __global__ void __launch_bounds__(256, 2) fwd_megakernel(Params P) {
;     ...
;   cg::grid_group grid = cg::this_grid();
;   if (threadIdx.x == 0) xb_words = make_uint4(0u, 0u, 0u, 0u);
;   __syncthreads();
;   const XcdBarrier xb = xcd_barrier_post((unsigned*)(P.ws + OFF_BAR), (volatile LAS unsigned*)&xb_words);
;     ...
;   run_phase<0>(P, 0, smem);
;   grid.sync();
;   if (PROBE_REP == 10) { run_phase<0>(P, 0, smem); GSYNC(); }
;   if (PROBE_REP == 11) { for (int i = 0; i < 40; ++i) GSYNC(); }
;   for (int l = 0; l < DEPTH; ++l) {
;     if (PROBE_REP == 1) { run_phase<1>(P, l, smem); GSYNC(); }
;     run_phase<1>(P, l, smem); GSYNC();
.LBB0_620:
	s_or_b64 exec, exec, s[0:1]
	v_bfe_u32 v2, v0, 10, 10
	v_bfe_u32 v0, v0, 20, 10
	v_or3_b32 v3, v148, v2, v0
	v_cmp_eq_u32_e32 vcc, 0, v3
	s_waitcnt lgkmcnt(0)
	s_barrier
	v_readlane_b32 s4, v253, 3
	v_readlane_b32 s5, v253, 4
	s_barrier
	s_load_dwordx4 s[12:15], s[4:5], 0xb0
	s_lshr_b32 s0, s62, 16
	v_writelane_b32 v253, s0, 10
	s_and_b32 s0, s62, 0xffff
	v_mad_u32_u24 v149, v0, s0, v2
	s_waitcnt lgkmcnt(0)
	s_add_u32 s2, s14, 0x1d005000
	s_addc_u32 s3, s15, 0
	v_writelane_b32 v253, s2, 11
	v_mbcnt_hi_u32_b32 v175, -1, v1
	v_mov_b32_e32 v151, 0
	v_writelane_b32 v253, s3, 12
	s_add_u32 s2, s14, 0x1c500000
	s_addc_u32 s3, s15, 0
	v_writelane_b32 v253, s2, 13
	v_bitop3_b32 v0, v175, 8, 15 bitop3:8
	v_mov_b32_e32 v152, -1
	v_writelane_b32 v253, s3, 14
	s_add_u32 s2, s14, 0x1c300000
	s_addc_u32 s3, s15, 0
	v_writelane_b32 v253, s2, 15
	v_mov_b32_e32 v172, 0x12140
	v_mov_b32_e32 v173, 0x12144
	v_writelane_b32 v253, s3, 16
	s_add_u32 s2, s14, 0x1c100000
	s_addc_u32 s3, s15, 0
	v_writelane_b32 v253, s2, 17
	v_mov_b32_e32 v174, 1
	v_add_lshl_u32 v176, v0, v175, 2
	v_writelane_b32 v253, s3, 18
	s_add_u32 s2, s14, 0x16900000
	s_addc_u32 s3, s15, 0
	s_add_u32 s34, s14, 0x9d00000
	v_writelane_b32 v253, s2, 19
	s_addc_u32 s35, s15, 0
	v_mov_b32_e32 v177, 0x12000
	v_writelane_b32 v253, s3, 20
	s_add_u32 s2, s10, 0x1c801200
	s_addc_u32 s3, s11, 0
	v_writelane_b32 v253, s2, 21
	v_mov_b32_e32 v178, 0x12040
	v_mov_b32_e32 v179, 0x358637bd
	v_writelane_b32 v253, s3, 22
	s_add_u32 s2, s10, 0x1c801400
	s_addc_u32 s3, s11, 0
	v_writelane_b32 v253, s2, 23
	v_mov_b32_e32 v180, 0x100
	v_mov_b32_e32 v181, 0x109c0
	v_writelane_b32 v253, s3, 24
	s_add_u32 s2, s10, 0x1c801500
	s_addc_u32 s3, s11, 0
	v_writelane_b32 v253, s2, 25
	v_mov_b32_e32 v182, 0x109c4
	v_mov_b32_e32 v183, 0x109c8
	v_writelane_b32 v253, s3, 26
	s_add_u32 s2, s10, 0x1c801600
	s_addc_u32 s3, s11, 0
	v_writelane_b32 v253, s2, 27
	v_mov_b32_e32 v184, 0x10900
	v_mov_b32_e32 v216, v151
	v_writelane_b32 v253, s3, 28
	s_add_u32 s2, s10, 0x1c801700
	s_addc_u32 s3, s11, 0
	v_writelane_b32 v253, s2, 29
	v_mov_b32_e32 v217, v151
	v_mov_b32_e32 v218, v151
	v_writelane_b32 v253, s3, 30
	s_add_u32 s2, s10, 0x1c801800
	s_addc_u32 s3, s11, 0
	v_writelane_b32 v253, s2, 31
	v_mov_b32_e32 v185, 0x800
	v_mov_b32_e32 v186, 0x10100
	v_writelane_b32 v253, s3, 32
	s_add_u32 s2, s10, 0x1c801900
	s_addc_u32 s3, s11, 0
	v_writelane_b32 v253, s2, 33
	v_mov_b32_e32 v153, v152
	v_mov_b32_e32 v187, 0xff800000
	v_writelane_b32 v253, s3, 34
	s_add_u32 s2, s10, 0x1c801a00
	s_addc_u32 s3, s11, 0
	v_writelane_b32 v253, s2, 35
	s_movk_i32 s36, 0x800
	s_movk_i32 s38, 0x3f3f
	v_writelane_b32 v253, s3, 36
	s_add_u32 s2, s10, 0x1c801b00
	s_addc_u32 s3, s11, 0
	v_writelane_b32 v253, s2, 37
	s_nop 1
	v_writelane_b32 v253, s3, 38
	s_add_u32 s2, s10, 0x1c801c00
	s_addc_u32 s3, s11, 0
	v_writelane_b32 v253, s2, 39
	s_nop 1
	v_writelane_b32 v253, s3, 40
	s_add_u32 s2, s10, 0x1c801d00
	s_addc_u32 s3, s11, 0
	v_writelane_b32 v253, s2, 41
	s_nop 1
	v_writelane_b32 v253, s3, 42
	s_add_u32 s2, s10, 0x1c801e00
	s_addc_u32 s3, s11, 0
	v_writelane_b32 v253, s2, 43
	s_nop 1
	v_writelane_b32 v253, s3, 44
	s_add_u32 s2, s10, 0x1c801f00
	s_addc_u32 s3, s11, 0
	v_writelane_b32 v253, s2, 45
	s_nop 1
	v_writelane_b32 v253, s3, 46
	s_add_u32 s2, s10, 0x1c802000
	s_addc_u32 s3, s11, 0
	v_writelane_b32 v253, s2, 47
	s_nop 1
	v_writelane_b32 v253, s3, 48
	s_add_u32 s2, s10, 0x1c802100
	s_addc_u32 s3, s11, 0
	v_writelane_b32 v253, s2, 49
	s_nop 1
	v_writelane_b32 v253, s3, 50
	s_add_u32 s2, s10, 0x1c802200
	s_addc_u32 s3, s11, 0
	v_writelane_b32 v253, s2, 51
	s_nop 1
	v_writelane_b32 v253, s3, 52
	s_add_u32 s2, s10, 0x1c802300
	s_addc_u32 s3, s11, 0
	v_writelane_b32 v253, s2, 53
	s_cmp_eq_u32 s33, 15
	s_nop 0
	v_writelane_b32 v253, s3, 54
	s_cselect_b64 s[2:3], -1, 0
	v_writelane_b32 v253, s2, 55
	s_cmp_eq_u32 s33, 14
	s_nop 0
	v_writelane_b32 v253, s3, 56
	s_cselect_b64 s[2:3], -1, 0
	v_writelane_b32 v253, s2, 57
	s_cmp_eq_u32 s33, 13
	s_nop 0
	v_writelane_b32 v253, s3, 58
	s_cselect_b64 s[2:3], -1, 0
	v_writelane_b32 v253, s2, 59
	s_cmp_eq_u32 s33, 12
	s_nop 0
	v_writelane_b32 v253, s3, 60
	s_cselect_b64 s[2:3], -1, 0
	v_writelane_b32 v253, s2, 61
	s_cmp_eq_u32 s33, 11
	s_nop 0
	v_writelane_b32 v253, s3, 62
	s_cselect_b64 s[2:3], -1, 0
	v_writelane_b32 v253, s2, 63
	s_cmp_eq_u32 s33, 10
	s_nop 0
	v_writelane_b32 v254, s3, 0
	s_cselect_b64 s[2:3], -1, 0
	v_writelane_b32 v254, s2, 1
	s_cmp_eq_u32 s33, 9
	s_nop 0
	v_writelane_b32 v254, s3, 2
	s_cselect_b64 s[2:3], -1, 0
	v_writelane_b32 v254, s2, 3
	s_cmp_eq_u32 s33, 8
	s_nop 0
	v_writelane_b32 v254, s3, 4
	s_cselect_b64 s[2:3], -1, 0
	v_writelane_b32 v254, s2, 5
	s_cmp_eq_u32 s33, 7
	s_nop 0
	v_writelane_b32 v254, s3, 6
	s_cselect_b64 s[2:3], -1, 0
	v_writelane_b32 v254, s2, 7
	s_cmp_eq_u32 s33, 6
	s_nop 0
	v_writelane_b32 v254, s3, 8
	s_cselect_b64 s[2:3], -1, 0
	v_writelane_b32 v254, s2, 9
	s_cmp_eq_u32 s33, 5
	s_nop 0
	v_writelane_b32 v254, s3, 10
	s_cselect_b64 s[2:3], -1, 0
	v_writelane_b32 v254, s2, 11
	s_cmp_eq_u32 s33, 4
	s_nop 0
	v_writelane_b32 v254, s3, 12
	s_cselect_b64 s[2:3], -1, 0
	v_writelane_b32 v254, s2, 13
	s_cmp_eq_u32 s33, 3
	s_nop 0
	v_writelane_b32 v254, s3, 14
	s_cselect_b64 s[2:3], -1, 0
	v_writelane_b32 v254, s2, 15
	s_cmp_eq_u32 s33, 2
	s_nop 0
	v_writelane_b32 v254, s3, 16
	s_cselect_b64 s[2:3], -1, 0
	v_writelane_b32 v254, s2, 17
	s_cmp_eq_u32 s33, 1
	s_nop 0
	v_writelane_b32 v254, s3, 18
	s_cselect_b64 s[2:3], -1, 0
	v_writelane_b32 v254, s2, 19
	s_cmp_eq_u32 s33, 0
	s_nop 0
	v_writelane_b32 v254, s3, 20
	s_cselect_b64 s[2:3], -1, 0
	s_lshl_b32 s1, s33, 8
	v_writelane_b32 v254, s2, 21
	s_add_u32 s1, s16, s1
	s_mov_b32 s33, 0xffff
	v_writelane_b32 v254, s3, 22
	s_addc_u32 s2, s17, 0
	s_add_u32 s6, s1, 0x1400
	s_addc_u32 s7, s2, 0
	v_writelane_b32 v254, s6, 23
	s_nop 1
	v_writelane_b32 v254, s7, 24
	s_add_u32 s6, s1, 0x2400
	s_addc_u32 s7, s2, 0
	v_writelane_b32 v254, s6, 25
	s_add_u32 s2, s10, 0x1c804400
	s_addc_u32 s3, s11, 0
	v_writelane_b32 v254, s7, 26
	v_writelane_b32 v254, s2, 27
	v_readlane_b32 s6, v253, 1
	v_readlane_b32 s7, v253, 2
	v_writelane_b32 v254, s3, 28
	s_add_u32 s2, s10, 0x1c804500
	s_addc_u32 s3, s11, 0
	v_writelane_b32 v254, s2, 29
	s_mul_i32 s1, s7, s6
	s_nop 0
	v_writelane_b32 v254, s3, 30
	s_load_dword s2, s[4:5], 0x158
	s_waitcnt lgkmcnt(0)
; DI unsigned xb_ld(unsigned* p)              { return __hip_atomic_load(p, __ATOMIC_RELAXED, __HIP_MEMORY_SCOPE_AGENT); }
; DI unsigned xb_add(unsigned* p, unsigned v) { return __hip_atomic_fetch_add(p, v, __ATOMIC_RELAXED, __HIP_MEMORY_SCOPE_AGENT); }
; #define XB_SPIN(cond, bar) do { unsigned _sp = 0; while (cond) { __builtin_amdgcn_s_sleep(1); \
;     if ((++_sp & 255u) == 0u) { if (xb_ld(&(bar)[XB_TMO])) break; if (_sp > XB_SPIN_CAP) { atomicAdd(&(bar)[XB_TMO], 1u); break; } } } } while (0)
; DI void xcd_barrier(const XcdBarrier& b) {
;   asm volatile("s_waitcnt vmcnt(0)" ::: "memory");
;   __syncthreads();
;   if (threadIdx.x == 0) {
;     unsigned* bar = b.bar;
;     __builtin_amdgcn_s_waitcnt(0);
;     unsigned nloc = b.st[0], nx = b.st[1];
;     if (nloc == 0u) { xcd_barrier_complete(bar, b.x, nloc, nx); b.st[0] = nloc; b.st[1] = nx; }
;     const unsigned old = xb_add(&bar[XB_XSUB(b.x)], 1u);
;     const unsigned gen = old / nloc;
;     if (old + 1u == (gen + 1u) * nloc) {
;       __builtin_amdgcn_fence(__ATOMIC_RELEASE, "agent");
;       asm volatile("s_waitcnt vmcnt(0)" ::: "memory");
;       const unsigned og = xb_add(&bar[XB_TOP], 1u);
;       const unsigned tg = og / nx;
;       if (og + 1u == (tg + 1u) * nx) xb_add(&bar[XB_TOPGEN], 1u);
;       else XB_SPIN(xb_ld(&bar[XB_TOPGEN]) == tg, bar);
;       __builtin_amdgcn_fence(__ATOMIC_ACQUIRE, "agent");
;       xb_add(&bar[XB_XGEN(b.x)], 1u);
;       asm volatile("s_waitcnt vmcnt(0)" ::: "memory");
;     } else {
;       XB_SPIN(xb_ld(&bar[XB_XGEN(b.x)]) == gen, bar);
;       __builtin_amdgcn_fence(__ATOMIC_ACQUIRE, "agent");
;       asm volatile("s_waitcnt vmcnt(0)" ::: "memory");
;     }
;   }
;   __syncthreads();
; }
; __global__ void __launch_bounds__(256, 2) fwd_megakernel(Params P) {
;     ...
;   grid.sync();
	s_mul_i32 s1, s1, s2
	v_writelane_b32 v254, s1, 31
	s_add_u32 s1, s14, 0x1c800000
	v_writelane_b32 v254, s1, 32
	s_addc_u32 s1, s15, 0
	s_add_u32 s2, s14, 0x9d00800
	v_writelane_b32 v254, s1, 33
	s_addc_u32 s3, s15, 0
	s_lshl_b32 s0, s0, 8
	v_writelane_b32 v254, s2, 34
	s_add_u32 s30, s14, 0x1b900000
	s_addc_u32 s31, s15, 0
	v_writelane_b32 v254, s3, 35
	v_writelane_b32 v254, s0, 36
	s_add_u32 s0, s14, 0x9d01000
	s_addc_u32 s1, s15, 0
	v_writelane_b32 v254, s0, 37
	s_brev_b32 s3, 1
	s_nop 0
	v_writelane_b32 v254, s1, 38
	s_add_u32 s0, s14, 0x1c805000
	s_addc_u32 s1, s15, 0
	v_writelane_b32 v254, s0, 39
	s_nop 1
	v_writelane_b32 v254, s1, 40
	s_add_u32 s0, s14, 0x1c600000
	s_addc_u32 s1, s15, 0
	v_writelane_b32 v254, s0, 41
	s_nop 1
	v_writelane_b32 v254, s1, 42
	s_add_u32 s0, s14, 0x19900000
	s_addc_u32 s1, s15, 0
	v_writelane_b32 v254, s0, 43
	s_nop 1
	v_writelane_b32 v254, s1, 44
	s_add_u32 s0, s14, 0x1c700000
	s_addc_u32 s1, s15, 0
	v_writelane_b32 v254, s0, 45
	s_ashr_i32 s27, s26, 31
	s_nop 0
	v_writelane_b32 v254, s1, 46
	v_writelane_b32 v254, s26, 47
	s_lshl_b32 s0, s6, 3
	s_nop 0
	v_writelane_b32 v254, s27, 48
	v_writelane_b32 v254, s0, 49
	s_add_u32 s0, s14, 0x9dcc480
	s_addc_u32 s1, s15, 0
	v_writelane_b32 v254, s0, 50
	s_mov_b32 s27, 0
	s_mov_b32 s8, s27
	v_writelane_b32 v254, s1, 51
	s_add_u32 s0, s14, 0x1b900400
	s_addc_u32 s1, s15, 0
	v_writelane_b32 v254, s0, 52
	s_nop 1
	v_writelane_b32 v254, s1, 53
	s_lshl_b32 s0, s6, 9
	v_writelane_b32 v254, s0, 54
	s_add_u32 s0, s14, 0x9d01b40
	v_writelane_b32 v254, s12, 55
	s_load_dwordx2 s[6:7], s[4:5], 0x58
	s_addc_u32 s1, s15, 0
	v_writelane_b32 v254, s13, 56
	v_writelane_b32 v254, s14, 57
	v_writelane_b32 v254, s15, 58
	s_load_dwordx4 s[12:15], s[4:5], 0x48
	v_writelane_b32 v254, s0, 59
	s_nop 1
	v_writelane_b32 v254, s1, 60
	s_waitcnt lgkmcnt(0)
	v_writelane_b32 v254, s6, 61
	s_movk_i32 s0, 0x3300
	s_nop 0
	v_writelane_b32 v254, s7, 62
	v_writelane_b32 v254, s12, 63
	s_nop 1
	v_writelane_b32 v252, s13, 0
	v_writelane_b32 v252, s14, 1
	v_writelane_b32 v252, s15, 2
	s_load_dwordx4 s[12:15], s[4:5], 0x0
	s_waitcnt lgkmcnt(0)
	v_writelane_b32 v252, s12, 3
	s_nop 1
	v_writelane_b32 v252, s13, 4
	v_writelane_b32 v252, s14, 5
	v_writelane_b32 v252, s15, 6
	s_load_dwordx8 s[12:19], s[4:5], 0x28
	s_waitcnt lgkmcnt(0)
	v_writelane_b32 v252, s12, 7
	s_nop 1
	v_writelane_b32 v252, s13, 8
	v_writelane_b32 v252, s14, 9
	v_writelane_b32 v252, s15, 10
	v_writelane_b32 v252, s16, 11
	v_writelane_b32 v252, s17, 12
	v_writelane_b32 v252, s18, 13
	v_writelane_b32 v252, s19, 14
	v_writelane_b32 v252, s34, 15
	s_nop 1
	v_writelane_b32 v252, s35, 16
	v_writelane_b32 v252, s30, 17
	s_nop 1
	v_writelane_b32 v252, s31, 18
	s_waitcnt vmcnt(0)
	s_waitcnt lgkmcnt(0)
	s_barrier
	s_mov_b64 s[4:5], exec
	v_readlane_b32 s6, v253, 7
	v_readlane_b32 s7, v253, 8
	s_and_b64 s[6:7], s[4:5], s[6:7]
	s_mov_b64 exec, s[6:7]
	s_cbranch_execz .Lgs0_1310
	s_waitcnt vmcnt(0) expcnt(0) lgkmcnt(0)
	ds_read_b32 v2, v172
	ds_read_b32 v0, v173
	s_waitcnt lgkmcnt(1)
	v_cmp_ne_u32_e32 vcc, 0, v2
	s_cbranch_vccnz .Lgs0_1274
	s_mov_b32 s1, 1
	s_branch .Lgs0_1262

; DI unsigned xb_ld(unsigned* p)              { return __hip_atomic_load(p, __ATOMIC_RELAXED, __HIP_MEMORY_SCOPE_AGENT); }
; DI unsigned xb_add(unsigned* p, unsigned v) { return __hip_atomic_fetch_add(p, v, __ATOMIC_RELAXED, __HIP_MEMORY_SCOPE_AGENT); }
; #define XB_SPIN(cond, bar) do { unsigned _sp = 0; while (cond) { __builtin_amdgcn_s_sleep(1); \
;     if ((++_sp & 255u) == 0u) { if (xb_ld(&(bar)[XB_TMO])) break; if (_sp > XB_SPIN_CAP) { atomicAdd(&(bar)[XB_TMO], 1u); break; } } } } while (0)
; DI void xcd_barrier(const XcdBarrier& b) {
;   asm volatile("s_waitcnt vmcnt(0)" ::: "memory");
;   __syncthreads();
;   if (threadIdx.x == 0) {
;     unsigned* bar = b.bar;
;     __builtin_amdgcn_s_waitcnt(0);
;     unsigned nloc = b.st[0], nx = b.st[1];
;     if (nloc == 0u) { xcd_barrier_complete(bar, b.x, nloc, nx); b.st[0] = nloc; b.st[1] = nx; }
;     const unsigned old = xb_add(&bar[XB_XSUB(b.x)], 1u);
;     const unsigned gen = old / nloc;
;     if (old + 1u == (gen + 1u) * nloc) {
;       __builtin_amdgcn_fence(__ATOMIC_RELEASE, "agent");
;       asm volatile("s_waitcnt vmcnt(0)" ::: "memory");
;       const unsigned og = xb_add(&bar[XB_TOP], 1u);
;       const unsigned tg = og / nx;
;       if (og + 1u == (tg + 1u) * nx) xb_add(&bar[XB_TOPGEN], 1u);
;       else XB_SPIN(xb_ld(&bar[XB_TOPGEN]) == tg, bar);
;       __builtin_amdgcn_fence(__ATOMIC_ACQUIRE, "agent");
;       xb_add(&bar[XB_XGEN(b.x)], 1u);
;       asm volatile("s_waitcnt vmcnt(0)" ::: "memory");
;     } else {
;       XB_SPIN(xb_ld(&bar[XB_XGEN(b.x)]) == gen, bar);
;       __builtin_amdgcn_fence(__ATOMIC_ACQUIRE, "agent");
;       asm volatile("s_waitcnt vmcnt(0)" ::: "memory");
;     }
;   }
;   __syncthreads();
; }
.Lgs0_1310:
	s_or_b64 exec, exec, s[4:5]
	s_waitcnt lgkmcnt(0)
	v_mov_b32_e32 v0, v148
	v_readlane_b32 s2, v253, 0
	s_barrier
	s_mov_b32 s8, 0
	s_branch .LBB0_634
